# setup phase: attention bias-table builder issues its 4 masked rpb loads together (one wait, one scalar pointer load) instead of 4 serialized load-wait blocks
# speedup vs baseline: 1.0131x; 1.0025x over previous
; __device__ __forceinline__ void attn_table(ArgsP a, int gt, int NGT) {
;     ...
;     for (int o = gt; o < 2 * 8 * 16 * 4 * 16 * 64; o += NGT) {
;         const int lane = o & 63, it = (o >> 6) & 15, qt = (o >> 10) & 3, h = (o >> 12) & 15, v = (o >> 16) & 7, i = o >> 19;
;         const int ii = it >> 1, t = it & 1, fr = lane & 15, fq = lane >> 4, kc0 = qt == 0 ? 0 : (qt == 1 ? 8 : (qt == 2 ? 24 : 32));
;         const int c = 16 * qt + fr, cs = min(max(c - 8, 0), 48); f32x4 w;
; #pragma unroll
;         for (int e = 0; e < 4; ++e) { const int kc = kc0 + 16 * t + 4 * fq + e; const bool valid = (kc >= cs) && (kc < cs + 16);
;             w[e] = valid ? a->rpb[((size_t)(i * 16 + h) * 15 + (ii - v + 7)) * 31 + (kc - c + 15)] * 1.4426950408889634f : -1e30f; }
;         *(f32x4*)(TB + (size_t)o * 4) = w;
.LBB0_92:
	s_or_b64 exec, exec, s[4:5]
	v_lshl_or_b32 v14, v2, 4, v1
	v_sub_u32_e64 v2, v14, 8 clamp
	v_min_u32_e32 v16, 48, v2
	v_lshrrev_b32_e32 v2, 2, v7
	v_and_b32_e32 v2, 28, v2
	v_bfe_u32 v4, v7, 12, 4
	v_add_u32_e32 v15, v3, v2
	v_ashrrev_i32_e32 v2, 15, v7
	v_bfe_u32 v5, v7, 16, 3
	v_bfe_u32 v10, v7, 7, 3
	v_and_or_b32 v2, v2, s18, v4
	v_mul_i32_i24_e32 v2, 15, v2
	v_sub_u32_e32 v4, v10, v5
	v_ashrrev_i32_e32 v3, 31, v2
	v_add_u32_e32 v10, 7, v4
	v_lshl_add_u64 v[2:3], v[2:3], 0, v[10:11]
	v_add_u32_e32 v17, 16, v16
	v_mad_u64_u32 v[12:13], s[4:5], v2, s19, 0
	v_mad_i32_i24 v13, v3, s19, v13
	s_load_dwordx2 s[10:11], s[14:15], 0xa0
	v_mov_b32_e32 v2, 0xf149f2ca
	v_mov_b32_e32 v3, 0xf149f2ca
	v_mov_b32_e32 v4, 0xf149f2ca
	v_mov_b32_e32 v5, 0xf149f2ca
	v_sub_u32_e32 v18, v15, v14
	v_ashrrev_i32_e32 v19, 31, v18
	s_waitcnt lgkmcnt(0)
	v_lshl_add_u64 v[20:21], s[10:11], 0, v[12:13]
	v_lshl_add_u64 v[20:21], v[18:19], 2, v[20:21]
	s_mov_b64 s[4:5], exec
	v_cmp_ge_u32_e32 vcc, v15, v16
	v_cmp_lt_u32_e64 s[10:11], v15, v17
	s_and_b64 vcc, vcc, s[10:11]
	s_and_b64 exec, s[4:5], vcc
	global_load_dword v2, v[20:21], off offset:60
	s_mov_b64 exec, s[4:5]
	v_or_b32_e32 v22, 1, v15
	v_cmp_ge_u32_e32 vcc, v22, v16
	v_cmp_lt_u32_e64 s[10:11], v22, v17
	s_and_b64 vcc, vcc, s[10:11]
	s_and_b64 exec, s[4:5], vcc
	global_load_dword v3, v[20:21], off offset:64
	s_mov_b64 exec, s[4:5]
	v_or_b32_e32 v22, 2, v15
	v_cmp_ge_u32_e32 vcc, v22, v16
	v_cmp_lt_u32_e64 s[10:11], v22, v17
	s_and_b64 vcc, vcc, s[10:11]
	s_and_b64 exec, s[4:5], vcc
	global_load_dword v4, v[20:21], off offset:68
	s_mov_b64 exec, s[4:5]
	v_or_b32_e32 v22, 3, v15
	v_cmp_ge_u32_e32 vcc, v22, v16
	v_cmp_lt_u32_e64 s[10:11], v22, v17
	s_and_b64 vcc, vcc, s[10:11]
	s_and_b64 exec, s[4:5], vcc
	global_load_dword v5, v[20:21], off offset:72
	s_mov_b64 exec, s[4:5]
	s_waitcnt vmcnt(0)
	v_cmp_ge_u32_e32 vcc, v15, v16
	v_cmp_lt_u32_e64 s[10:11], v15, v17
	s_and_b64 vcc, vcc, s[10:11]
	s_and_b64 exec, s[4:5], vcc
	v_mul_f32_e32 v2, 0x3fb8aa3b, v2
	s_mov_b64 exec, s[4:5]
	v_or_b32_e32 v22, 1, v15
	v_cmp_ge_u32_e32 vcc, v22, v16
	v_cmp_lt_u32_e64 s[10:11], v22, v17
	s_and_b64 vcc, vcc, s[10:11]
	s_and_b64 exec, s[4:5], vcc
	v_mul_f32_e32 v3, 0x3fb8aa3b, v3
	s_mov_b64 exec, s[4:5]
	v_or_b32_e32 v22, 2, v15
	v_cmp_ge_u32_e32 vcc, v22, v16
	v_cmp_lt_u32_e64 s[10:11], v22, v17
	s_and_b64 vcc, vcc, s[10:11]
	s_and_b64 exec, s[4:5], vcc
	v_mul_f32_e32 v4, 0x3fb8aa3b, v4
	s_mov_b64 exec, s[4:5]
	v_or_b32_e32 v22, 3, v15
	v_cmp_ge_u32_e32 vcc, v22, v16
	v_cmp_lt_u32_e64 s[10:11], v22, v17
	s_and_b64 vcc, vcc, s[10:11]
	s_and_b64 exec, s[4:5], vcc
	v_mul_f32_e32 v5, 0x3fb8aa3b, v5
	s_mov_b64 exec, s[4:5]
	s_branch .LBB0_85
